# GU1 SwiGLU epilogue: the 8 row-scale loads issued together with one wait (were serialized by the compiler)
# baseline (speedup 1.0000x reference)
; __device__ __forceinline__ float rstd_of(u64 ss) { return rsqrtf((float)ss * (1.0f / 4294967296.0f) * (1.0f / DM) + EPS); }
;     __device__ __forceinline__ void operator()(const f32x4 (&acc)[2][2][4][2], const pg8::Unit& u, int wr, int wc, int fr, int fq) const {
;         const int row0 = u.pm * 256 + wr * 64 + fr, col0 = u.pn * 128 + wc * 32 + 8 * fq;
;         float rsv[2][4];
; #pragma unroll
;         for (int ai = 0; ai < 2; ++ai)
; #pragma unroll
;             for (int m = 0; m < 4; ++m) rsv[ai][m] = rstd_of(ss[row0 + ai * 128 + m * 16]);
;         __builtin_amdgcn_sched_barrier(0);
.LBB0_176:
	v_lshl_add_u32 v140, s6, 8, v143
	v_readlane_b32 s6, v255, 18
	v_ashrrev_i32_e32 v141, 31, v140
	v_readlane_b32 s7, v255, 19
	v_or_b32_e32 v159, 16, v140
	v_or_b32_e32 v158, 32, v140
	v_lshl_add_u64 v[156:157], v[140:141], 3, s[6:7]
	global_load_dwordx2 v[164:165], v[156:157], off
	global_load_dwordx2 v[166:167], v[156:157], off offset:128
	global_load_dwordx2 v[168:169], v[156:157], off offset:256
	global_load_dwordx2 v[170:171], v[156:157], off offset:384
	global_load_dwordx2 v[172:173], v[156:157], off offset:1024
	global_load_dwordx2 v[174:175], v[156:157], off offset:1152
	global_load_dwordx2 v[176:177], v[156:157], off offset:1280
	global_load_dwordx2 v[178:179], v[156:157], off offset:1408
	v_add_u32_e32 v153, 0x80, v140
	v_lshl_or_b32 v162, s2, 7, v147
	v_add_u32_e32 v151, 0x90, v140
	v_or_b32_e32 v155, 48, v140
	v_add_u32_e32 v160, 0xb0, v140
	s_waitcnt vmcnt(0)
	v_ffbh_u32_e32 v180, v165
	v_ffbh_u32_e32 v181, v167
	v_ffbh_u32_e32 v182, v169
	v_ffbh_u32_e32 v183, v171
	v_ffbh_u32_e32 v184, v173
	v_ffbh_u32_e32 v185, v175
	v_ffbh_u32_e32 v186, v177
	v_ffbh_u32_e32 v187, v179
	v_min_u32_e32 v180, 32, v180
	v_min_u32_e32 v181, 32, v181
	v_min_u32_e32 v182, 32, v182
	v_min_u32_e32 v183, 32, v183
	v_min_u32_e32 v184, 32, v184
	v_min_u32_e32 v185, 32, v185
	v_min_u32_e32 v186, 32, v186
	v_min_u32_e32 v187, 32, v187
	v_lshlrev_b64 v[164:165], v180, v[164:165]
	v_lshlrev_b64 v[166:167], v181, v[166:167]
	v_lshlrev_b64 v[168:169], v182, v[168:169]
	v_lshlrev_b64 v[170:171], v183, v[170:171]
	v_lshlrev_b64 v[172:173], v184, v[172:173]
	v_lshlrev_b64 v[174:175], v185, v[174:175]
	v_lshlrev_b64 v[176:177], v186, v[176:177]
	v_lshlrev_b64 v[178:179], v187, v[178:179]
	v_min_u32_e32 v188, 1, v164
	v_min_u32_e32 v189, 1, v166
	v_min_u32_e32 v190, 1, v168
	v_min_u32_e32 v191, 1, v170
	v_min_u32_e32 v192, 1, v172
	v_min_u32_e32 v193, 1, v174
	v_min_u32_e32 v194, 1, v176
	v_min_u32_e32 v195, 1, v178
	v_or_b32_e32 v188, v165, v188
	v_or_b32_e32 v189, v167, v189
	v_or_b32_e32 v190, v169, v190
	v_or_b32_e32 v191, v171, v191
	v_or_b32_e32 v192, v173, v192
	v_or_b32_e32 v193, v175, v193
	v_or_b32_e32 v194, v177, v194
	v_or_b32_e32 v195, v179, v195
	v_cvt_f32_u32_e32 v188, v188
	v_cvt_f32_u32_e32 v189, v189
	v_cvt_f32_u32_e32 v190, v190
	v_cvt_f32_u32_e32 v191, v191
	v_cvt_f32_u32_e32 v192, v192
	v_cvt_f32_u32_e32 v193, v193
	v_cvt_f32_u32_e32 v194, v194
	v_cvt_f32_u32_e32 v195, v195
	v_sub_u32_e32 v180, 32, v180
	v_sub_u32_e32 v181, 32, v181
	v_sub_u32_e32 v182, 32, v182
	v_sub_u32_e32 v183, 32, v183
	v_sub_u32_e32 v184, 32, v184
	v_sub_u32_e32 v185, 32, v185
	v_sub_u32_e32 v186, 32, v186
	v_sub_u32_e32 v187, 32, v187
	v_ldexp_f32 v188, v188, v180
	v_ldexp_f32 v189, v189, v181
	v_ldexp_f32 v190, v190, v182
	v_ldexp_f32 v191, v191, v183
	v_ldexp_f32 v192, v192, v184
	v_ldexp_f32 v193, v193, v185
	v_ldexp_f32 v194, v194, v186
	v_ldexp_f32 v195, v195, v187
	v_mul_f32_e32 v188, 0x2f800000, v188
	v_mul_f32_e32 v189, 0x2f800000, v189
	v_mul_f32_e32 v190, 0x2f800000, v190
	v_mul_f32_e32 v191, 0x2f800000, v191
	v_mul_f32_e32 v192, 0x2f800000, v192
	v_mul_f32_e32 v193, 0x2f800000, v193
	v_mul_f32_e32 v194, 0x2f800000, v194
	v_mul_f32_e32 v195, 0x2f800000, v195
	v_fmamk_f32 v188, v188, 0x3a000000, v238
	v_fmamk_f32 v189, v189, 0x3a000000, v238
	v_fmamk_f32 v190, v190, 0x3a000000, v238
	v_fmamk_f32 v191, v191, 0x3a000000, v238
	v_fmamk_f32 v192, v192, 0x3a000000, v238
	v_fmamk_f32 v193, v193, 0x3a000000, v238
	v_fmamk_f32 v194, v194, 0x3a000000, v238
	v_fmamk_f32 v195, v195, 0x3a000000, v238
	v_cmp_gt_f32_e32 vcc, s34, v188
	v_mul_f32_e32 v180, 0x4b800000, v188
	s_nop 0
	v_cndmask_b32_e32 v188, v188, v180, vcc
	v_rsq_f32_e32 v188, v188
	s_nop 0
	v_mul_f32_e32 v180, 0x45800000, v188
	v_cndmask_b32_e32 v152, v188, v180, vcc
	v_cmp_gt_f32_e32 vcc, s34, v189
	v_mul_f32_e32 v181, 0x4b800000, v189
	s_nop 0
	v_cndmask_b32_e32 v189, v189, v181, vcc
	v_rsq_f32_e32 v189, v189
	s_nop 0
	v_mul_f32_e32 v181, 0x45800000, v189
	v_cndmask_b32_e32 v150, v189, v181, vcc
	v_cmp_gt_f32_e32 vcc, s34, v190
	v_mul_f32_e32 v182, 0x4b800000, v190
	s_nop 0
	v_cndmask_b32_e32 v190, v190, v182, vcc
	v_rsq_f32_e32 v190, v190
	s_nop 0
	v_mul_f32_e32 v182, 0x45800000, v190
	v_cndmask_b32_e32 v148, v190, v182, vcc
	v_cmp_gt_f32_e32 vcc, s34, v191
	v_mul_f32_e32 v183, 0x4b800000, v191
	s_nop 0
	v_cndmask_b32_e32 v191, v191, v183, vcc
	v_rsq_f32_e32 v191, v191
	s_nop 0
	v_mul_f32_e32 v183, 0x45800000, v191
	v_cndmask_b32_e32 v146, v191, v183, vcc
	v_cmp_gt_f32_e32 vcc, s34, v192
	v_mul_f32_e32 v184, 0x4b800000, v192
	s_nop 0
	v_cndmask_b32_e32 v192, v192, v184, vcc
	v_rsq_f32_e32 v192, v192
	s_nop 0
	v_mul_f32_e32 v184, 0x45800000, v192
	v_cndmask_b32_e32 v144, v192, v184, vcc
	v_cmp_gt_f32_e32 vcc, s34, v193
	v_mul_f32_e32 v185, 0x4b800000, v193
	s_nop 0
	v_cndmask_b32_e32 v193, v193, v185, vcc
	v_rsq_f32_e32 v193, v193
	s_nop 0
	v_mul_f32_e32 v185, 0x45800000, v193
	v_cndmask_b32_e32 v142, v193, v185, vcc
	v_cmp_gt_f32_e32 vcc, s34, v194
	v_mul_f32_e32 v186, 0x4b800000, v194
	s_nop 0
	v_cndmask_b32_e32 v194, v194, v186, vcc
	v_rsq_f32_e32 v194, v194
	s_nop 0
	v_mul_f32_e32 v186, 0x45800000, v194
	v_cndmask_b32_e32 v154, v194, v186, vcc
	v_cmp_gt_f32_e32 vcc, s34, v195
	v_mul_f32_e32 v187, 0x4b800000, v195
	s_nop 0
	v_cndmask_b32_e32 v195, v195, v187, vcc
	v_rsq_f32_e32 v195, v195
	s_nop 0
	v_mul_f32_e32 v187, 0x45800000, v195
	v_cndmask_b32_e32 v156, v195, v187, vcc
	v_add_u32_e32 v141, 0xa0, v140
	v_pk_mul_f32 v[126:127], v[126:127], v[152:153] op_sel_hi:[1,0]
	v_pk_mul_f32 v[122:123], v[122:123], v[152:153] op_sel_hi:[1,0]
	v_mul_f32_e32 v157, 0xbfb8aa3b, v126
	v_exp_f32_e32 v164, v157
; __device__ __forceinline__ unsigned cvt_pk_bf16(float lo, float hi) { unsigned r; asm volatile("v_cvt_pk_bf16_f32 %0, %1, %2" : "=v"(r) : "v"(lo), "v"(hi)); return r; }
;     __device__ __forceinline__ void operator()(const f32x4 (&acc)[2][2][4][2], const pg8::Unit& u, int wr, int wc, int fr, int fq) const {
;     ...
; #pragma unroll
;         for (int ai = 0; ai < 2; ++ai)
; #pragma unroll
;             for (int m = 0; m < 4; ++m) {
;                 const int row = row0 + ai * 128 + m * 16; const float rs = rsv[ai][m];
;                 const f32x4 g0 = acc[ai][0][m][0] * rs, g1 = acc[ai][0][m][1] * rs, u0 = acc[ai][1][m][0] * rs, u1 = acc[ai][1][m][1] * rs;
;                 const f32x4 t0 = g0 * (-LOG2E), t1 = g1 * (-LOG2E);
;                 f32x4 e0, e1;
; #pragma unroll
;                 for (int e = 0; e < 4; ++e) { e0[e] = __builtin_amdgcn_exp2f(t0[e]); e1[e] = __builtin_amdgcn_exp2f(t1[e]); }
;                 e0 = e0 + 1.0f; e1 = e1 + 1.0f;
;                 f32x4 r0, r1;
; #pragma unroll
;                 for (int e = 0; e < 4; ++e) { r0[e] = __builtin_amdgcn_rcpf(e0[e]); r1[e] = __builtin_amdgcn_rcpf(e1[e]); }
;                 const f32x4 o0 = (g0 * r0) * u0, o1 = (g1 * r1) * u1;
;                 u32x4 w; w.x = pg8::cvt_pk_bf16(o0[0], o0[1]); w.y = pg8::cvt_pk_bf16(o0[2], o0[3]); w.z = pg8::cvt_pk_bf16(o1[0], o1[1]); w.w = pg8::cvt_pk_bf16(o1[2], o1[3]);
;                 *(u32x4*)(act + (size_t)row * DFF + col0) = w;
	v_mul_f32_e32 v157, 0xbfb8aa3b, v122
	v_exp_f32_e32 v166, v157
	v_mul_f32_e32 v157, 0xbfb8aa3b, v127
	v_pk_mul_f32 v[128:129], v[128:129], v[152:153] op_sel_hi:[1,0]
	v_exp_f32_e32 v165, v157
	v_mul_f32_e32 v157, 0xbfb8aa3b, v123
	v_pk_mul_f32 v[124:125], v[124:125], v[152:153] op_sel_hi:[1,0]
	v_exp_f32_e32 v167, v157
	v_mul_f32_e32 v157, 0xbfb8aa3b, v128
	v_exp_f32_e32 v168, v157
	v_mul_f32_e32 v157, 0xbfb8aa3b, v124
	v_exp_f32_e32 v170, v157
	v_mul_f32_e32 v157, 0xbfb8aa3b, v129
	v_exp_f32_e32 v169, v157
	v_mul_f32_e32 v157, 0xbfb8aa3b, v125
	v_exp_f32_e32 v171, v157
	v_pk_add_f32 v[164:165], v[164:165], 1.0 op_sel_hi:[1,0]
	v_pk_add_f32 v[168:169], v[168:169], 1.0 op_sel_hi:[1,0]
	v_pk_add_f32 v[166:167], v[166:167], 1.0 op_sel_hi:[1,0]
	v_pk_add_f32 v[170:171], v[170:171], 1.0 op_sel_hi:[1,0]
	v_rcp_f32_e32 v164, v164
	v_rcp_f32_e32 v166, v166
	v_rcp_f32_e32 v165, v165
	v_rcp_f32_e32 v167, v167
	v_rcp_f32_e32 v168, v168
	v_rcp_f32_e32 v169, v169
	v_rcp_f32_e32 v170, v170
	v_rcp_f32_e32 v171, v171
	v_pk_mul_f32 v[118:119], v[118:119], v[152:153] op_sel_hi:[1,0]
	v_pk_mul_f32 v[120:121], v[120:121], v[152:153] op_sel_hi:[1,0]
	v_pk_mul_f32 v[114:115], v[114:115], v[152:153] op_sel_hi:[1,0]
	v_pk_mul_f32 v[126:127], v[126:127], v[164:165]
	v_pk_mul_f32 v[128:129], v[128:129], v[168:169]
	v_pk_mul_f32 v[122:123], v[122:123], v[166:167]
	v_pk_mul_f32 v[116:117], v[116:117], v[152:153] op_sel_hi:[1,0]
	v_pk_mul_f32 v[120:121], v[120:121], v[128:129]
	v_pk_mul_f32 v[118:119], v[118:119], v[126:127]
	v_pk_mul_f32 v[124:125], v[124:125], v[170:171]
	v_pk_mul_f32 v[114:115], v[114:115], v[122:123]
	v_ashrrev_i32_e32 v163, 31, v162
	v_pk_mul_f32 v[116:117], v[116:117], v[124:125]
	v_cvt_pk_bf16_f32 v118, v118, v119
	v_cvt_pk_bf16_f32 v119, v120, v121
	v_cvt_pk_bf16_f32 v120, v114, v115
	v_mov_b64_e32 v[114:115], s[62:63]
	v_cvt_pk_bf16_f32 v121, v116, v117
	v_mad_i64_i32 v[122:123], s[6:7], v140, s59, v[114:115]
	v_lshlrev_b64 v[116:117], 1, v[162:163]
	v_lshl_add_u64 v[122:123], v[122:123], 0, v[116:117]
	v_pk_mul_f32 v[106:107], v[106:107], v[150:151] op_sel_hi:[1,0]
	global_store_dwordx4 v[122:123], v[118:121], off
	v_pk_mul_f32 v[110:111], v[110:111], v[150:151] op_sel_hi:[1,0]
	v_pk_mul_f32 v[108:109], v[108:109], v[150:151] op_sel_hi:[1,0]
	v_mul_f32_e32 v119, 0xbfb8aa3b, v106
	v_mul_f32_e32 v118, 0xbfb8aa3b, v110
	v_exp_f32_e32 v120, v119
	v_mul_f32_e32 v119, 0xbfb8aa3b, v111
	v_pk_mul_f32 v[112:113], v[112:113], v[150:151] op_sel_hi:[1,0]
	v_exp_f32_e32 v118, v118
	v_exp_f32_e32 v119, v119
	v_mul_f32_e32 v121, 0xbfb8aa3b, v107
	v_mul_f32_e32 v123, 0xbfb8aa3b, v108
	v_mul_f32_e32 v125, 0xbfb8aa3b, v109
	v_exp_f32_e32 v121, v121
	v_mul_f32_e32 v122, 0xbfb8aa3b, v112
	v_exp_f32_e32 v124, v123
	v_mul_f32_e32 v123, 0xbfb8aa3b, v113
	v_exp_f32_e32 v125, v125
	v_exp_f32_e32 v122, v122
	v_exp_f32_e32 v123, v123
	v_pk_add_f32 v[118:119], v[118:119], 1.0 op_sel_hi:[1,0]
	v_pk_add_f32 v[124:125], v[124:125], 1.0 op_sel_hi:[1,0]
	v_pk_add_f32 v[120:121], v[120:121], 1.0 op_sel_hi:[1,0]
	v_rcp_f32_e32 v118, v118
	v_rcp_f32_e32 v119, v119
	v_pk_add_f32 v[122:123], v[122:123], 1.0 op_sel_hi:[1,0]
	v_rcp_f32_e32 v120, v120
	v_rcp_f32_e32 v121, v121
	v_rcp_f32_e32 v124, v124
	v_rcp_f32_e32 v125, v125
	v_rcp_f32_e32 v122, v122
	v_rcp_f32_e32 v123, v123
	v_pk_mul_f32 v[102:103], v[102:103], v[150:151] op_sel_hi:[1,0]
	v_pk_mul_f32 v[110:111], v[110:111], v[118:119]
	v_pk_mul_f32 v[98:99], v[98:99], v[150:151] op_sel_hi:[1,0]
	v_pk_mul_f32 v[100:101], v[100:101], v[150:151] op_sel_hi:[1,0]
	v_pk_mul_f32 v[102:103], v[102:103], v[110:111]
	v_pk_mul_f32 v[106:107], v[106:107], v[120:121]
	v_pk_mul_f32 v[108:109], v[108:109], v[124:125]
	v_pk_mul_f32 v[104:105], v[104:105], v[150:151] op_sel_hi:[1,0]
	v_pk_mul_f32 v[112:113], v[112:113], v[122:123]
	v_pk_mul_f32 v[108:109], v[100:101], v[108:109]
	v_pk_mul_f32 v[100:101], v[98:99], v[106:107]
	v_cvt_pk_bf16_f32 v98, v102, v103
	v_mad_i64_i32 v[102:103], s[6:7], v159, s59, v[114:115]
	v_pk_mul_f32 v[104:105], v[104:105], v[112:113]
	v_lshl_add_u64 v[102:103], v[102:103], 0, v[116:117]
	v_cvt_pk_bf16_f32 v99, v104, v105
	v_pk_mul_f32 v[90:91], v[90:91], v[148:149] op_sel_hi:[1,0]
	v_cvt_pk_bf16_f32 v100, v100, v101
	v_cvt_pk_bf16_f32 v101, v108, v109
	global_store_dwordx4 v[102:103], v[98:101], off
	v_pk_mul_f32 v[94:95], v[94:95], v[148:149] op_sel_hi:[1,0]
	v_pk_mul_f32 v[92:93], v[92:93], v[148:149] op_sel_hi:[1,0]
	v_mul_f32_e32 v99, 0xbfb8aa3b, v90
	v_mul_f32_e32 v98, 0xbfb8aa3b, v94
	v_exp_f32_e32 v100, v99
	v_mul_f32_e32 v99, 0xbfb8aa3b, v95
	v_pk_mul_f32 v[96:97], v[96:97], v[148:149] op_sel_hi:[1,0]
	v_exp_f32_e32 v98, v98
	v_exp_f32_e32 v99, v99
	v_mul_f32_e32 v101, 0xbfb8aa3b, v91
	v_mul_f32_e32 v103, 0xbfb8aa3b, v92
	v_mul_f32_e32 v105, 0xbfb8aa3b, v93
	v_exp_f32_e32 v101, v101
	v_mul_f32_e32 v102, 0xbfb8aa3b, v96
	v_exp_f32_e32 v104, v103
	v_mul_f32_e32 v103, 0xbfb8aa3b, v97
	v_exp_f32_e32 v105, v105
	v_exp_f32_e32 v102, v102
	v_exp_f32_e32 v103, v103
	v_pk_add_f32 v[98:99], v[98:99], 1.0 op_sel_hi:[1,0]
	v_pk_add_f32 v[104:105], v[104:105], 1.0 op_sel_hi:[1,0]
	v_pk_add_f32 v[100:101], v[100:101], 1.0 op_sel_hi:[1,0]
	v_rcp_f32_e32 v98, v98
	v_rcp_f32_e32 v99, v99
	v_pk_add_f32 v[102:103], v[102:103], 1.0 op_sel_hi:[1,0]
	v_rcp_f32_e32 v100, v100
	v_rcp_f32_e32 v101, v101
	v_rcp_f32_e32 v104, v104
	v_rcp_f32_e32 v105, v105
	v_rcp_f32_e32 v102, v102
	v_rcp_f32_e32 v103, v103
	v_pk_mul_f32 v[86:87], v[86:87], v[148:149] op_sel_hi:[1,0]
	v_pk_mul_f32 v[94:95], v[94:95], v[98:99]
	v_pk_mul_f32 v[82:83], v[82:83], v[148:149] op_sel_hi:[1,0]
	v_pk_mul_f32 v[84:85], v[84:85], v[148:149] op_sel_hi:[1,0]
; __device__ __forceinline__ unsigned cvt_pk_bf16(float lo, float hi) { unsigned r; asm volatile("v_cvt_pk_bf16_f32 %0, %1, %2" : "=v"(r) : "v"(lo), "v"(hi)); return r; }
;     __device__ __forceinline__ void operator()(const f32x4 (&acc)[2][2][4][2], const pg8::Unit& u, int wr, int wc, int fr, int fq) const {
;     ...
; #pragma unroll
;         for (int ai = 0; ai < 2; ++ai)
; #pragma unroll
;             for (int m = 0; m < 4; ++m) {
;                 const int row = row0 + ai * 128 + m * 16; const float rs = rsv[ai][m];
;                 const f32x4 g0 = acc[ai][0][m][0] * rs, g1 = acc[ai][0][m][1] * rs, u0 = acc[ai][1][m][0] * rs, u1 = acc[ai][1][m][1] * rs;
;                 const f32x4 t0 = g0 * (-LOG2E), t1 = g1 * (-LOG2E);
;                 f32x4 e0, e1;
; #pragma unroll
;                 for (int e = 0; e < 4; ++e) { e0[e] = __builtin_amdgcn_exp2f(t0[e]); e1[e] = __builtin_amdgcn_exp2f(t1[e]); }
;                 e0 = e0 + 1.0f; e1 = e1 + 1.0f;
;                 f32x4 r0, r1;
; #pragma unroll
;                 for (int e = 0; e < 4; ++e) { r0[e] = __builtin_amdgcn_rcpf(e0[e]); r1[e] = __builtin_amdgcn_rcpf(e1[e]); }
;                 const f32x4 o0 = (g0 * r0) * u0, o1 = (g1 * r1) * u1;
;                 u32x4 w; w.x = pg8::cvt_pk_bf16(o0[0], o0[1]); w.y = pg8::cvt_pk_bf16(o0[2], o0[3]); w.z = pg8::cvt_pk_bf16(o1[0], o1[1]); w.w = pg8::cvt_pk_bf16(o1[2], o1[3]);
;                 *(u32x4*)(act + (size_t)row * DFF + col0) = w;
	v_pk_mul_f32 v[86:87], v[86:87], v[94:95]
	v_pk_mul_f32 v[90:91], v[90:91], v[100:101]
	v_pk_mul_f32 v[92:93], v[92:93], v[104:105]
	v_pk_mul_f32 v[88:89], v[88:89], v[148:149] op_sel_hi:[1,0]
	v_pk_mul_f32 v[96:97], v[96:97], v[102:103]
	v_pk_mul_f32 v[92:93], v[84:85], v[92:93]
	v_pk_mul_f32 v[84:85], v[82:83], v[90:91]
	v_cvt_pk_bf16_f32 v82, v86, v87
	v_mad_i64_i32 v[86:87], s[6:7], v158, s59, v[114:115]
	v_pk_mul_f32 v[88:89], v[88:89], v[96:97]
	v_lshl_add_u64 v[86:87], v[86:87], 0, v[116:117]
	v_cvt_pk_bf16_f32 v83, v88, v89
	v_pk_mul_f32 v[74:75], v[74:75], v[146:147] op_sel_hi:[1,0]
	v_cvt_pk_bf16_f32 v84, v84, v85
	v_cvt_pk_bf16_f32 v85, v92, v93
	global_store_dwordx4 v[86:87], v[82:85], off
	v_pk_mul_f32 v[78:79], v[78:79], v[146:147] op_sel_hi:[1,0]
	v_pk_mul_f32 v[76:77], v[76:77], v[146:147] op_sel_hi:[1,0]
	v_mul_f32_e32 v83, 0xbfb8aa3b, v74
	v_mul_f32_e32 v82, 0xbfb8aa3b, v78
	v_exp_f32_e32 v84, v83
	v_mul_f32_e32 v83, 0xbfb8aa3b, v79
	v_pk_mul_f32 v[80:81], v[80:81], v[146:147] op_sel_hi:[1,0]
	v_exp_f32_e32 v82, v82
	v_exp_f32_e32 v83, v83
	v_mul_f32_e32 v85, 0xbfb8aa3b, v75
	v_mul_f32_e32 v87, 0xbfb8aa3b, v76
	v_mul_f32_e32 v89, 0xbfb8aa3b, v77
	v_exp_f32_e32 v85, v85
	v_mul_f32_e32 v86, 0xbfb8aa3b, v80
	v_exp_f32_e32 v88, v87
	v_mul_f32_e32 v87, 0xbfb8aa3b, v81
	v_exp_f32_e32 v89, v89
	v_exp_f32_e32 v86, v86
	v_exp_f32_e32 v87, v87
	v_pk_add_f32 v[82:83], v[82:83], 1.0 op_sel_hi:[1,0]
	v_pk_add_f32 v[88:89], v[88:89], 1.0 op_sel_hi:[1,0]
	v_pk_add_f32 v[84:85], v[84:85], 1.0 op_sel_hi:[1,0]
	v_rcp_f32_e32 v82, v82
	v_rcp_f32_e32 v83, v83
	v_pk_add_f32 v[86:87], v[86:87], 1.0 op_sel_hi:[1,0]
	v_rcp_f32_e32 v84, v84
	v_rcp_f32_e32 v85, v85
	v_rcp_f32_e32 v88, v88
	v_rcp_f32_e32 v89, v89
	v_rcp_f32_e32 v86, v86
	v_rcp_f32_e32 v87, v87
	v_pk_mul_f32 v[70:71], v[70:71], v[146:147] op_sel_hi:[1,0]
	v_pk_mul_f32 v[78:79], v[78:79], v[82:83]
	v_pk_mul_f32 v[66:67], v[66:67], v[146:147] op_sel_hi:[1,0]
	v_pk_mul_f32 v[68:69], v[68:69], v[146:147] op_sel_hi:[1,0]
	v_pk_mul_f32 v[70:71], v[70:71], v[78:79]
	v_pk_mul_f32 v[74:75], v[74:75], v[84:85]
	v_pk_mul_f32 v[76:77], v[76:77], v[88:89]
	v_pk_mul_f32 v[72:73], v[72:73], v[146:147] op_sel_hi:[1,0]
	v_pk_mul_f32 v[80:81], v[80:81], v[86:87]
	v_pk_mul_f32 v[76:77], v[68:69], v[76:77]
	v_pk_mul_f32 v[68:69], v[66:67], v[74:75]
	v_cvt_pk_bf16_f32 v66, v70, v71
	v_mad_i64_i32 v[70:71], s[6:7], v155, s59, v[114:115]
	v_pk_mul_f32 v[72:73], v[72:73], v[80:81]
	v_lshl_add_u64 v[70:71], v[70:71], 0, v[116:117]
	v_cvt_pk_bf16_f32 v67, v72, v73
	v_pk_mul_f32 v[58:59], v[58:59], v[144:145] op_sel_hi:[1,0]
	v_cvt_pk_bf16_f32 v68, v68, v69
	v_cvt_pk_bf16_f32 v69, v76, v77
	global_store_dwordx4 v[70:71], v[66:69], off
	v_pk_mul_f32 v[62:63], v[62:63], v[144:145] op_sel_hi:[1,0]
	v_pk_mul_f32 v[60:61], v[60:61], v[144:145] op_sel_hi:[1,0]
	v_mul_f32_e32 v67, 0xbfb8aa3b, v58
	v_mul_f32_e32 v66, 0xbfb8aa3b, v62
	v_exp_f32_e32 v68, v67
	v_mul_f32_e32 v67, 0xbfb8aa3b, v63
	v_pk_mul_f32 v[64:65], v[64:65], v[144:145] op_sel_hi:[1,0]
	v_exp_f32_e32 v66, v66
	v_exp_f32_e32 v67, v67
	v_mul_f32_e32 v69, 0xbfb8aa3b, v59
	v_mul_f32_e32 v71, 0xbfb8aa3b, v60
	v_mul_f32_e32 v73, 0xbfb8aa3b, v61
	v_exp_f32_e32 v69, v69
	v_mul_f32_e32 v70, 0xbfb8aa3b, v64
	v_exp_f32_e32 v72, v71
	v_mul_f32_e32 v71, 0xbfb8aa3b, v65
	v_exp_f32_e32 v73, v73
	v_exp_f32_e32 v70, v70
	v_exp_f32_e32 v71, v71
	v_pk_add_f32 v[66:67], v[66:67], 1.0 op_sel_hi:[1,0]
	v_pk_add_f32 v[72:73], v[72:73], 1.0 op_sel_hi:[1,0]
	v_pk_add_f32 v[68:69], v[68:69], 1.0 op_sel_hi:[1,0]
	v_rcp_f32_e32 v66, v66
	v_rcp_f32_e32 v67, v67
	v_pk_add_f32 v[70:71], v[70:71], 1.0 op_sel_hi:[1,0]
	v_rcp_f32_e32 v68, v68
	v_rcp_f32_e32 v69, v69
	v_rcp_f32_e32 v72, v72
	v_rcp_f32_e32 v73, v73
	v_rcp_f32_e32 v70, v70
	v_rcp_f32_e32 v71, v71
	v_pk_mul_f32 v[54:55], v[54:55], v[144:145] op_sel_hi:[1,0]
	v_pk_mul_f32 v[62:63], v[62:63], v[66:67]
	v_pk_mul_f32 v[50:51], v[50:51], v[144:145] op_sel_hi:[1,0]
	v_pk_mul_f32 v[52:53], v[52:53], v[144:145] op_sel_hi:[1,0]
	v_pk_mul_f32 v[54:55], v[54:55], v[62:63]
	v_pk_mul_f32 v[58:59], v[58:59], v[68:69]
	v_pk_mul_f32 v[60:61], v[60:61], v[72:73]
	v_pk_mul_f32 v[56:57], v[56:57], v[144:145] op_sel_hi:[1,0]
	v_pk_mul_f32 v[64:65], v[64:65], v[70:71]
	v_pk_mul_f32 v[60:61], v[52:53], v[60:61]
	v_pk_mul_f32 v[52:53], v[50:51], v[58:59]
	v_cvt_pk_bf16_f32 v50, v54, v55
	v_mad_i64_i32 v[54:55], s[6:7], v153, s59, v[114:115]
	v_pk_mul_f32 v[56:57], v[56:57], v[64:65]
	v_lshl_add_u64 v[54:55], v[54:55], 0, v[116:117]
	v_cvt_pk_bf16_f32 v51, v56, v57
	v_pk_mul_f32 v[42:43], v[42:43], v[142:143] op_sel_hi:[1,0]
	v_cvt_pk_bf16_f32 v52, v52, v53
	v_cvt_pk_bf16_f32 v53, v60, v61
	global_store_dwordx4 v[54:55], v[50:53], off
	v_pk_mul_f32 v[46:47], v[46:47], v[142:143] op_sel_hi:[1,0]
	v_pk_mul_f32 v[44:45], v[44:45], v[142:143] op_sel_hi:[1,0]
	v_mul_f32_e32 v51, 0xbfb8aa3b, v42
	v_mul_f32_e32 v50, 0xbfb8aa3b, v46
	v_exp_f32_e32 v52, v51
	v_mul_f32_e32 v51, 0xbfb8aa3b, v47
	v_pk_mul_f32 v[48:49], v[48:49], v[142:143] op_sel_hi:[1,0]
	v_exp_f32_e32 v50, v50
	v_exp_f32_e32 v51, v51
	v_mul_f32_e32 v53, 0xbfb8aa3b, v43
	v_mul_f32_e32 v55, 0xbfb8aa3b, v44
	v_mul_f32_e32 v57, 0xbfb8aa3b, v45
	v_exp_f32_e32 v53, v53
	v_mul_f32_e32 v54, 0xbfb8aa3b, v48
	v_exp_f32_e32 v56, v55
	v_mul_f32_e32 v55, 0xbfb8aa3b, v49
	v_exp_f32_e32 v57, v57
	v_exp_f32_e32 v54, v54
	v_exp_f32_e32 v55, v55
; __device__ __forceinline__ unsigned cvt_pk_bf16(float lo, float hi) { unsigned r; asm volatile("v_cvt_pk_bf16_f32 %0, %1, %2" : "=v"(r) : "v"(lo), "v"(hi)); return r; }
; #define PG8_BAR __builtin_amdgcn_s_barrier()
; template <class Epi, class Sched, bool ALIGN_EPI = false, bool SP2 = false>
; __device__ __forceinline__ void gemm_phase(LAS unsigned char* lds, const Gemm g, const Sched& S, const Epi& E) {
;     ...
;         if constexpr (ALIGN_EPI) { if (wr == 0) PG8_BAR; }
;         E(acc, cur, wr, wc, fr, fq); S.done(cur);
;         if (!has_next) break;
; #pragma unroll
;         for (int a = 0; a < 2; ++a)
; #pragma unroll
;             for (int b = 0; b < 2; ++b)
; #pragma unroll
;                 for (int m = 0; m < 4; ++m)
; #pragma unroll
;                     for (int n = 0; n < 2; ++n) acc[a][b][m][n] = (f32x4){0.f, 0.f, 0.f, 0.f};
;         cur = nxt; cA = nA; cB = nB; ++ui;
;         if constexpr (ALIGN_EPI) { if (wr == 1) PG8_BAR; }
;     __device__ __forceinline__ void operator()(const f32x4 (&acc)[2][2][4][2], const pg8::Unit& u, int wr, int wc, int fr, int fq) const {
;     ...
; #pragma unroll
;         for (int ai = 0; ai < 2; ++ai)
; #pragma unroll
;             for (int m = 0; m < 4; ++m) {
;                 const int row = row0 + ai * 128 + m * 16; const float rs = rsv[ai][m];
;                 const f32x4 g0 = acc[ai][0][m][0] * rs, g1 = acc[ai][0][m][1] * rs, u0 = acc[ai][1][m][0] * rs, u1 = acc[ai][1][m][1] * rs;
;                 const f32x4 t0 = g0 * (-LOG2E), t1 = g1 * (-LOG2E);
;                 f32x4 e0, e1;
; #pragma unroll
;                 for (int e = 0; e < 4; ++e) { e0[e] = __builtin_amdgcn_exp2f(t0[e]); e1[e] = __builtin_amdgcn_exp2f(t1[e]); }
;                 e0 = e0 + 1.0f; e1 = e1 + 1.0f;
;                 f32x4 r0, r1;
; #pragma unroll
;                 for (int e = 0; e < 4; ++e) { r0[e] = __builtin_amdgcn_rcpf(e0[e]); r1[e] = __builtin_amdgcn_rcpf(e1[e]); }
;                 const f32x4 o0 = (g0 * r0) * u0, o1 = (g1 * r1) * u1;
;                 u32x4 w; w.x = pg8::cvt_pk_bf16(o0[0], o0[1]); w.y = pg8::cvt_pk_bf16(o0[2], o0[3]); w.z = pg8::cvt_pk_bf16(o1[0], o1[1]); w.w = pg8::cvt_pk_bf16(o1[2], o1[3]);
;                 *(u32x4*)(act + (size_t)row * DFF + col0) = w;
;             }
	v_pk_add_f32 v[50:51], v[50:51], 1.0 op_sel_hi:[1,0]
	v_pk_add_f32 v[56:57], v[56:57], 1.0 op_sel_hi:[1,0]
	v_pk_add_f32 v[52:53], v[52:53], 1.0 op_sel_hi:[1,0]
	v_rcp_f32_e32 v50, v50
	v_rcp_f32_e32 v51, v51
	v_pk_add_f32 v[54:55], v[54:55], 1.0 op_sel_hi:[1,0]
	v_rcp_f32_e32 v52, v52
	v_rcp_f32_e32 v53, v53
	v_rcp_f32_e32 v56, v56
	v_rcp_f32_e32 v57, v57
	v_rcp_f32_e32 v54, v54
	v_rcp_f32_e32 v55, v55
	v_pk_mul_f32 v[38:39], v[38:39], v[142:143] op_sel_hi:[1,0]
	v_pk_mul_f32 v[46:47], v[46:47], v[50:51]
	v_pk_mul_f32 v[34:35], v[34:35], v[142:143] op_sel_hi:[1,0]
	v_pk_mul_f32 v[36:37], v[36:37], v[142:143] op_sel_hi:[1,0]
	v_pk_mul_f32 v[38:39], v[38:39], v[46:47]
	v_pk_mul_f32 v[42:43], v[42:43], v[52:53]
	v_pk_mul_f32 v[44:45], v[44:45], v[56:57]
	v_pk_mul_f32 v[40:41], v[40:41], v[142:143] op_sel_hi:[1,0]
	v_pk_mul_f32 v[48:49], v[48:49], v[54:55]
	v_pk_mul_f32 v[44:45], v[36:37], v[44:45]
	v_pk_mul_f32 v[36:37], v[34:35], v[42:43]
	v_cvt_pk_bf16_f32 v34, v38, v39
	v_mad_i64_i32 v[38:39], s[6:7], v151, s59, v[114:115]
	v_pk_mul_f32 v[40:41], v[40:41], v[48:49]
	v_lshl_add_u64 v[38:39], v[38:39], 0, v[116:117]
	v_cvt_pk_bf16_f32 v35, v40, v41
	v_pk_mul_f32 v[26:27], v[26:27], v[154:155] op_sel_hi:[1,0]
	v_cvt_pk_bf16_f32 v36, v36, v37
	v_cvt_pk_bf16_f32 v37, v44, v45
	global_store_dwordx4 v[38:39], v[34:37], off
	v_pk_mul_f32 v[30:31], v[30:31], v[154:155] op_sel_hi:[1,0]
	v_pk_mul_f32 v[28:29], v[28:29], v[154:155] op_sel_hi:[1,0]
	v_mul_f32_e32 v35, 0xbfb8aa3b, v26
	v_mul_f32_e32 v34, 0xbfb8aa3b, v30
	v_exp_f32_e32 v36, v35
	v_mul_f32_e32 v35, 0xbfb8aa3b, v31
	v_pk_mul_f32 v[32:33], v[32:33], v[154:155] op_sel_hi:[1,0]
	v_exp_f32_e32 v34, v34
	v_exp_f32_e32 v35, v35
	v_mul_f32_e32 v37, 0xbfb8aa3b, v27
	v_mul_f32_e32 v39, 0xbfb8aa3b, v28
	v_mul_f32_e32 v41, 0xbfb8aa3b, v29
	v_exp_f32_e32 v37, v37
	v_mul_f32_e32 v38, 0xbfb8aa3b, v32
	v_exp_f32_e32 v40, v39
	v_mul_f32_e32 v39, 0xbfb8aa3b, v33
	v_exp_f32_e32 v41, v41
	v_exp_f32_e32 v38, v38
	v_exp_f32_e32 v39, v39
	v_pk_add_f32 v[34:35], v[34:35], 1.0 op_sel_hi:[1,0]
	v_pk_add_f32 v[40:41], v[40:41], 1.0 op_sel_hi:[1,0]
	v_pk_add_f32 v[36:37], v[36:37], 1.0 op_sel_hi:[1,0]
	v_rcp_f32_e32 v34, v34
	v_rcp_f32_e32 v35, v35
	v_pk_add_f32 v[38:39], v[38:39], 1.0 op_sel_hi:[1,0]
	v_rcp_f32_e32 v36, v36
	v_rcp_f32_e32 v37, v37
	v_rcp_f32_e32 v40, v40
	v_rcp_f32_e32 v41, v41
	v_rcp_f32_e32 v38, v38
	v_rcp_f32_e32 v39, v39
	v_pk_mul_f32 v[22:23], v[22:23], v[154:155] op_sel_hi:[1,0]
	v_pk_mul_f32 v[30:31], v[30:31], v[34:35]
	v_pk_mul_f32 v[18:19], v[18:19], v[154:155] op_sel_hi:[1,0]
	v_pk_mul_f32 v[20:21], v[20:21], v[154:155] op_sel_hi:[1,0]
	v_pk_mul_f32 v[22:23], v[22:23], v[30:31]
	v_pk_mul_f32 v[26:27], v[26:27], v[36:37]
	v_pk_mul_f32 v[28:29], v[28:29], v[40:41]
	v_pk_mul_f32 v[24:25], v[24:25], v[154:155] op_sel_hi:[1,0]
	v_pk_mul_f32 v[32:33], v[32:33], v[38:39]
	v_pk_mul_f32 v[28:29], v[20:21], v[28:29]
	v_pk_mul_f32 v[20:21], v[18:19], v[26:27]
	v_cvt_pk_bf16_f32 v18, v22, v23
	v_mad_i64_i32 v[22:23], s[6:7], v141, s59, v[114:115]
	v_pk_mul_f32 v[24:25], v[24:25], v[32:33]
	v_lshl_add_u64 v[22:23], v[22:23], 0, v[116:117]
	v_cvt_pk_bf16_f32 v19, v24, v25
	v_pk_mul_f32 v[10:11], v[10:11], v[156:157] op_sel_hi:[1,0]
	v_cvt_pk_bf16_f32 v20, v20, v21
	v_cvt_pk_bf16_f32 v21, v28, v29
	global_store_dwordx4 v[22:23], v[18:21], off
	v_pk_mul_f32 v[14:15], v[14:15], v[156:157] op_sel_hi:[1,0]
	v_pk_mul_f32 v[12:13], v[12:13], v[156:157] op_sel_hi:[1,0]
	v_mul_f32_e32 v19, 0xbfb8aa3b, v10
	v_mul_f32_e32 v18, 0xbfb8aa3b, v14
	v_exp_f32_e32 v20, v19
	v_mul_f32_e32 v19, 0xbfb8aa3b, v15
	v_exp_f32_e32 v18, v18
	v_exp_f32_e32 v19, v19
	v_mul_f32_e32 v21, 0xbfb8aa3b, v11
	v_mul_f32_e32 v23, 0xbfb8aa3b, v12
	v_mul_f32_e32 v25, 0xbfb8aa3b, v13
	v_pk_mul_f32 v[16:17], v[16:17], v[156:157] op_sel_hi:[1,0]
	v_exp_f32_e32 v21, v21
	v_exp_f32_e32 v24, v23
	v_exp_f32_e32 v25, v25
	v_mul_f32_e32 v22, 0xbfb8aa3b, v16
	v_mul_f32_e32 v23, 0xbfb8aa3b, v17
	v_exp_f32_e32 v22, v22
	v_exp_f32_e32 v23, v23
	v_pk_add_f32 v[18:19], v[18:19], 1.0 op_sel_hi:[1,0]
	v_pk_add_f32 v[24:25], v[24:25], 1.0 op_sel_hi:[1,0]
	v_pk_add_f32 v[20:21], v[20:21], 1.0 op_sel_hi:[1,0]
	v_rcp_f32_e32 v18, v18
	v_rcp_f32_e32 v19, v19
	v_rcp_f32_e32 v20, v20
	v_rcp_f32_e32 v21, v21
	v_rcp_f32_e32 v24, v24
	v_rcp_f32_e32 v25, v25
	v_pk_add_f32 v[22:23], v[22:23], 1.0 op_sel_hi:[1,0]
	v_pk_mul_f32 v[6:7], v[6:7], v[156:157] op_sel_hi:[1,0]
	v_rcp_f32_e32 v22, v22
	v_rcp_f32_e32 v23, v23
	v_pk_mul_f32 v[14:15], v[14:15], v[18:19]
	v_pk_mul_f32 v[2:3], v[2:3], v[156:157] op_sel_hi:[1,0]
	v_pk_mul_f32 v[4:5], v[4:5], v[156:157] op_sel_hi:[1,0]
	v_pk_mul_f32 v[6:7], v[6:7], v[14:15]
	v_pk_mul_f32 v[10:11], v[10:11], v[20:21]
	v_pk_mul_f32 v[12:13], v[12:13], v[24:25]
	v_pk_mul_f32 v[8:9], v[8:9], v[156:157] op_sel_hi:[1,0]
	v_pk_mul_f32 v[12:13], v[4:5], v[12:13]
	v_pk_mul_f32 v[4:5], v[2:3], v[10:11]
	v_cvt_pk_bf16_f32 v2, v6, v7
	v_mad_i64_i32 v[6:7], s[6:7], v160, s59, v[114:115]
	v_pk_mul_f32 v[16:17], v[16:17], v[22:23]
	v_lshl_add_u64 v[6:7], v[6:7], 0, v[116:117]
	s_andn2_b64 vcc, exec, s[36:37]
	s_mov_b64 s[24:25], -1
	v_pk_mul_f32 v[8:9], v[8:9], v[16:17]
	s_nop 0
	v_cvt_pk_bf16_f32 v3, v8, v9
	v_cvt_pk_bf16_f32 v4, v4, v5
	v_cvt_pk_bf16_f32 v5, v12, v13
	global_store_dwordx4 v[6:7], v[2:5], off
	s_cbranch_vccnz .LBB0_169
	s_andn2_b64 vcc, exec, s[0:1]
	s_cbranch_vccnz .LBB0_168
	s_barrier
	s_branch .LBB0_168
